# v119 plus nt hint on LRU pass-3 read-once stream loads
# speedup vs baseline: 1.0037x; 1.0037x over previous
; #define GAS __attribute__((address_space(1)))
; template <int PASS>
; __device__ __forceinline__ void lru_unit(const LruPtrs& args, LAS unsigned char* lds, int chunk, int bl, int g, int ck) {
;     ...
; #pragma unroll
;         for (int i = 0; i < 4; ++i) { const int idx = lane + 64 * i, r = idx >> 3, ch = idx & 7;
;             gtile[i] = *(const GAS v4u*)(Z + ((size_t)bl * T + ck * 256 + w * 32 + r) * LDZ + ZC_GA + g * 64 + ch * 8); }
; #pragma unroll
;         for (int q = 0; q < 8; ++q) { const v4u st = stash[q * 64];
; #pragma unroll
;             for (int p = 0; p < 4; ++p) { av[q][p] = pg8::bf_lo(st[p]); uv[q][p] = pg8::bf_hi(st[p]); } }
;         if (w == 0) { const GAS unsigned* gs = (const GAS unsigned*)((GAS v4u*)(ws + WS_STASH) + ((size_t)((bl * 16 + g) * 32 + ck) * NWAVES) * 8 * 64);
; #pragma unroll
;             for (int ww = 0; ww < 8; ++ww) gagg[ww] = gs[(size_t)((ww * 8 + (lane >> 3)) * 64 + 31 + 32 * ((lane >> 2) & 1)) * 4 + (lane & 3)]; }
.Lq3_nopf:
	s_cmpk_gt_i32 s2, 0x3ff
	s_cbranch_scc0 .LBB0_557
	v_mov_b32_e32 v68, v236
	s_add_i32 s18, s2, 0xfffffc00
	s_lshr_b32 s41, s18, 9
	v_readfirstlane_b32 s15, v68
	s_bfe_u32 s42, s2, 0x40005
	s_and_b32 s40, s2, 31
	s_ashr_i32 s14, s15, 6
	s_mov_b64 s[8:9], s[12:13]
	s_add_u32 s6, s8, 0x13c00000
	s_addc_u32 s7, s9, 0
	s_add_u32 s43, s8, 0x29c00000
	s_addc_u32 s44, s9, 0
	s_and_b32 s18, s18, 0x1ffffe00
	s_lshl_b32 s45, s42, 5
	s_or_b32 s18, s45, s18
	s_or_b32 s18, s18, s40
	s_lshl_b32 s18, s18, 3
	s_ashr_i32 s45, s14, 31
	s_add_u32 s46, s14, s18
	s_addc_u32 s47, s45, 0
	s_lshl_b32 s45, s40, 8
	s_lshl_b32 s48, s14, 5
	s_lshl_b32 s49, s41, 13
	s_lshl_b64 s[46:47], s[46:47], 13
	s_or_b32 s45, s49, s45
	s_ashr_i32 s49, s48, 31
	s_add_u32 s45, s48, s45
	s_addc_u32 s48, s49, 0
	v_bfe_u32 v69, v68, 3, 3
	v_or_b32_e32 v2, s45, v69
	v_mov_b32_e32 v3, s48
	v_lshlrev_b32_e32 v0, 3, v68
	v_lshlrev_b64 v[4:5], 11, v[2:3]
	v_and_b32_e32 v0, 56, v0
	v_lshl_add_u64 v[4:5], s[6:7], 0, v[4:5]
	s_lshl_b32 s48, s42, 7
	s_mov_b32 s49, s19
	v_or_b32_e32 v6, 8, v2
	v_mov_b32_e32 v7, v3
	v_lshl_add_u64 v[4:5], v[4:5], 0, s[48:49]
	v_lshlrev_b32_e32 v0, 1, v0
	v_lshlrev_b64 v[6:7], 11, v[6:7]
	v_lshl_add_u64 v[52:53], v[4:5], 0, v[0:1]
	v_lshl_add_u64 v[6:7], s[6:7], 0, v[6:7]
	v_add_co_u32_e32 v4, vcc, s88, v52
	v_lshl_add_u64 v[6:7], v[6:7], 0, s[48:49]
	s_nop 0
	v_addc_co_u32_e32 v5, vcc, 0, v53, vcc
	v_lshl_add_u64 v[54:55], v[6:7], 0, v[0:1]
	v_add_co_u32_e32 v6, vcc, s88, v54
	v_and_b32_e32 v70, 63, v68
	s_nop 0
	v_addc_co_u32_e32 v7, vcc, 0, v55, vcc
	global_load_dwordx4 v[30:33], v[4:5], off
	global_load_dwordx4 v[34:37], v[6:7], off
	v_or_b32_e32 v4, 16, v2
	v_mov_b32_e32 v5, v3
	v_lshlrev_b64 v[4:5], 11, v[4:5]
	v_lshl_add_u64 v[4:5], s[6:7], 0, v[4:5]
	v_or_b32_e32 v2, 24, v2
	v_lshl_add_u64 v[4:5], v[4:5], 0, s[48:49]
	v_lshlrev_b64 v[2:3], 11, v[2:3]
	v_lshl_add_u64 v[56:57], v[4:5], 0, v[0:1]
	v_lshl_add_u64 v[2:3], s[6:7], 0, v[2:3]
	v_add_co_u32_e32 v4, vcc, s88, v56
	v_lshl_add_u64 v[2:3], v[2:3], 0, s[48:49]
	s_nop 0
	v_addc_co_u32_e32 v5, vcc, 0, v57, vcc
	v_lshl_add_u64 v[50:51], v[2:3], 0, v[0:1]
	v_add_co_u32_e32 v2, vcc, s88, v50
	s_add_u32 s6, s43, s46
	s_nop 0
	v_addc_co_u32_e32 v3, vcc, 0, v51, vcc
	global_load_dwordx4 v[42:45], v[4:5], off
	global_load_dwordx4 v[46:49], v[2:3], off nt
	s_addc_u32 s7, s44, s47
	v_lshlrev_b32_e32 v2, 4, v70
	v_mov_b32_e32 v3, v1
	v_lshl_add_u64 v[4:5], s[6:7], 0, v[2:3]
	global_load_dwordx4 v[38:41], v2, s[6:7] nt
	global_load_dwordx4 v[26:29], v2, s[6:7] offset:1024 nt
	global_load_dwordx4 v[22:25], v2, s[6:7] offset:2048 nt
	global_load_dwordx4 v[18:21], v2, s[6:7] offset:3072 nt
	v_add_co_u32_e32 v2, vcc, 0x1000, v4
	s_cmp_lt_u32 s15, 64
	s_nop 0
	v_addc_co_u32_e32 v3, vcc, 0, v5, vcc
	global_load_dwordx4 v[14:17], v[2:3], off nt
	global_load_dwordx4 v[10:13], v[2:3], off offset:1024 nt
	global_load_dwordx4 v[6:9], v[2:3], off offset:2048 nt
	s_nop 0
	global_load_dwordx4 v[2:5], v[2:3], off offset:3072 nt
	v_mov_b32_e32 v59, 0
	s_cselect_b64 s[6:7], -1, 0
	s_cmp_gt_u32 s15, 63
	v_mov_b32_e32 v77, 0
	v_mov_b32_e32 v75, 0
	v_mov_b32_e32 v74, 0
	v_mov_b32_e32 v73, 0
	v_mov_b32_e32 v72, 0
	v_mov_b32_e32 v71, 0
	v_mov_b32_e32 v76, 0
	s_cbranch_scc1 .LBB0_545
	v_lshlrev_b32_e32 v58, 5, v70
	v_lshlrev_b32_e32 v60, 5, v68
	s_lshl_b64 s[46:47], s[18:19], 13
	v_and_b32_e32 v58, 0x700, v58
	v_and_b32_e32 v60, 0x80, v60
	v_and_b32_e32 v61, 3, v68
	s_add_u32 s46, s43, s46
	v_or3_b32 v58, v60, v61, v58
	s_addc_u32 s47, s44, s47
	v_lshlrev_b32_e32 v60, 2, v58
	v_mov_b32_e32 v61, v1
	v_lshl_add_u64 v[62:63], s[46:47], 0, v[60:61]
	s_movk_i32 s18, 0x2000
	v_add_co_u32_e32 v64, vcc, s18, v62
	s_movk_i32 s18, 0x6000
	s_nop 0
	v_addc_co_u32_e32 v65, vcc, 0, v63, vcc
	v_add_co_u32_e32 v66, vcc, s31, v62
	s_nop 1
	v_addc_co_u32_e32 v67, vcc, 0, v63, vcc
	v_add_co_u32_e32 v72, vcc, s18, v62
	s_nop 1
	v_addc_co_u32_e32 v73, vcc, 0, v63, vcc
	v_add_co_u32_e32 v78, vcc, 0x8000, v62
	s_nop 1
	v_addc_co_u32_e32 v79, vcc, 0, v63, vcc
	v_add_co_u32_e32 v80, vcc, 0xa000, v62
	s_nop 1
	v_addc_co_u32_e32 v81, vcc, 0, v63, vcc
	v_add_co_u32_e32 v62, vcc, 0xc000, v62
	s_nop 1
	v_addc_co_u32_e32 v63, vcc, 0, v63, vcc
	global_load_dword v77, v60, s[46:47] offset:496
	global_load_dword v75, v[64:65], off offset:496
	global_load_dword v74, v[66:67], off offset:496
	s_nop 0
	global_load_dword v73, v[72:73], off offset:496
	s_nop 0
	global_load_dword v72, v[78:79], off offset:496
	global_load_dword v71, v[80:81], off offset:496
	global_load_dword v76, v[62:63], off offset:496
